# v55 + FoX tile loop: uniform cum load for the early-exit test hoisted from the tail (load->vmcnt(0)) to the loop head
# speedup vs baseline: 1.0022x; 1.0018x over previous
.LBB0_677:
	s_add_i32 s8, s26, 2
	s_cmp_lt_i32 s8, 1
	s_cbranch_scc1 .LBB0_698
	s_cmp_lg_u32 s26, -1
	s_cselect_b64 s[28:29], -1, 0
	s_cmp_eq_u32 s26, -1
	s_cbranch_scc1 .LBB0_682
	s_sub_i32 s2, s54, 63
	s_mov_b32 s3, 0
	s_lshl_b64 s[2:3], s[2:3], 2
	s_add_u32 s2, s0, s2
	s_addc_u32 s3, s1, s3
	global_load_dword v250, v1, s[2:3] offset:-4
	s_mov_b32 s27, s21
	s_lshl_b64 s[2:3], s[26:27], 14
	v_lshl_add_u64 v[66:67], v[140:141], 0, s[2:3]
	v_lshl_add_u64 v[68:69], v[136:137], 1, v[66:67]
	global_load_dwordx4 v[114:117], v[144:145], off
	global_load_dwordx4 v[122:125], v[142:143], off
	v_lshl_add_u64 v[66:67], v[138:139], 1, v[66:67]
	global_load_dwordx4 v[118:121], v[68:69], off
	global_load_dwordx4 v[126:129], v[66:67], off
	s_and_saveexec_b64 s[2:3], s[4:5]
	s_cbranch_execz .LBB0_681
	v_add_u32_e32 v66, s54, v134
	v_add_u32_e32 v66, 0xffffff81, v66
	v_ashrrev_i32_e32 v67, 31, v66
	v_lshl_add_u64 v[66:67], v[66:67], 2, s[0:1]
	global_load_dword v133, v[66:67], off

.LBB0_688:
	v_cndmask_b32_e64 v66, 0, 1, s[28:29]
	v_cmp_ne_u32_e64 s[8:9], 1, v66
	s_andn2_b64 vcc, exec, s[28:29]
	s_cbranch_vccnz .LBB0_694
	s_xor_b32 s2, s27, 1
	s_mul_i32 s3, s2, 0x4400
	v_add_u32_e32 v66, s3, v135
	s_mulk_i32 s2, 0x4800
	v_add_u32_e32 v67, s2, v147
	v_add_u32_e32 v68, v66, v148
	s_waitcnt vmcnt(3)
	ds_write_b128 v68, v[114:117]
	v_add_u32_e32 v68, v67, v149
	v_add_u32_e32 v66, v66, v150
	s_waitcnt vmcnt(1)
	ds_write_b128 v68, v[118:121] offset:34816
	ds_write_b128 v66, v[122:125]
	v_add_u32_e32 v66, v67, v151
	s_waitcnt vmcnt(0)
	ds_write_b128 v66, v[126:129] offset:34816
	s_and_saveexec_b64 s[2:3], s[4:5]
	s_lshl_b32 s28, s27, 8
	s_xor_b32 s28, s28, 0x100
	v_xor_b32_e32 v66, 0x80000000, v133
	v_add_u32_e32 v67, s28, v154
	ds_write_b32 v67, v66
	s_or_b64 exec, exec, s[2:3]
	v_mov_b32_e32 v66, v250
	s_mov_b32 s2, 0xc2200000
	v_sub_f32_e32 v66, v152, v66
	v_sub_f32_e32 v66, v66, v178
	v_cmp_gt_f32_e32 vcc, s2, v66
	s_mov_b64 s[2:3], exec
	s_and_saveexec_b64 s[28:29], s[6:7]
	s_cbranch_execz .LBB0_693
	s_cmp_eq_u64 vcc, s[2:3]
	s_cselect_b64 s[2:3], -1, 0
	v_cndmask_b32_e64 v66, 0, 1, s[2:3]
	s_lshl_b32 s2, s27, 5
	s_add_i32 s2, s35, s2
	v_mov_b32_e32 v67, s2
	ds_write_b32 v67, v66
